# band loops read V row-major from LDS with ds_read_b64_tr_b16 (V rows fetched by coalesced LDS-DMA like K); P4's V^T fragment-image builder for the sliding-window/dilated branches removed
# speedup vs baseline: 1.0424x; 1.0043x over previous
.LBB0_653:
	v_readlane_b32 s2, v254, 12
	v_readlane_b32 s3, v254, 13
	s_andn2_b64 vcc, exec, s[2:3]
	v_readlane_b32 s2, v254, 37
	v_and_b32_e32 v0, 63, v17
	s_mov_b32 s12, s2
	v_readlane_b32 s3, v254, 38
.LBB0_654:
	v_readlane_b32 s2, v254, 14
	v_readlane_b32 s3, v254, 15
	s_andn2_b64 vcc, exec, s[2:3]
	s_cbranch_vccnz .LBB0_657
	v_readlane_b32 s2, v254, 37
	s_mov_b32 s4, s2
	s_lshl_b32 s2, s2, 6
	s_add_i32 s12, s2, 0x200
	s_lshl_b32 s13, s68, 6
	s_mov_b32 s14, s4
	v_readlane_b32 s3, v254, 38

.Lband_entry:
	s_waitcnt vmcnt(0)
	v_lshlrev_b32_e32 v183, 2, v220
	v_add_u32_e32 v2, 0x10000, v183
	v_lshrrev_b32_e32 v183, 6, v220
	v_lshlrev_b32_e32 v183, 8, v183
	v_add_u32_e32 v183, 0x0, v183
	v_mov_b32_e32 v3, s2
	ds_write_b32 v183, v3 offset:0
	v_mov_b32_e32 v3, s3
	ds_write_b32 v183, v3 offset:4
	v_mov_b32_e32 v3, s4
	ds_write_b32 v183, v3 offset:8
	v_mov_b32_e32 v3, s5
	ds_write_b32 v183, v3 offset:12
	v_mov_b32_e32 v3, s6
	ds_write_b32 v183, v3 offset:16
	v_mov_b32_e32 v3, s7
	ds_write_b32 v183, v3 offset:20
	v_mov_b32_e32 v3, s8
	ds_write_b32 v183, v3 offset:24
	v_mov_b32_e32 v3, s9
	ds_write_b32 v183, v3 offset:28
	v_mov_b32_e32 v3, s10
	ds_write_b32 v183, v3 offset:32
	v_mov_b32_e32 v3, s11
	ds_write_b32 v183, v3 offset:36
	v_mov_b32_e32 v3, s12
	ds_write_b32 v183, v3 offset:40
	v_mov_b32_e32 v3, s13
	ds_write_b32 v183, v3 offset:44
	v_mov_b32_e32 v3, s14
	ds_write_b32 v183, v3 offset:48
	v_mov_b32_e32 v3, s15
	ds_write_b32 v183, v3 offset:52
	v_mov_b32_e32 v3, s16
	ds_write_b32 v183, v3 offset:56
	v_mov_b32_e32 v3, s17
	ds_write_b32 v183, v3 offset:60
	v_mov_b32_e32 v3, s18
	ds_write_b32 v183, v3 offset:64
	v_mov_b32_e32 v3, s19
	ds_write_b32 v183, v3 offset:68
	v_mov_b32_e32 v3, s20
	ds_write_b32 v183, v3 offset:72
	v_mov_b32_e32 v3, s21
	ds_write_b32 v183, v3 offset:76
	v_mov_b32_e32 v3, s22
	ds_write_b32 v183, v3 offset:80
	v_mov_b32_e32 v3, s23
	ds_write_b32 v183, v3 offset:84
	v_mov_b32_e32 v3, s24
	ds_write_b32 v183, v3 offset:88
	v_mov_b32_e32 v3, s25
	ds_write_b32 v183, v3 offset:92
	v_mov_b32_e32 v3, s26
	ds_write_b32 v183, v3 offset:96
	v_mov_b32_e32 v3, s27
	ds_write_b32 v183, v3 offset:100
	v_mov_b32_e32 v3, s28
	ds_write_b32 v183, v3 offset:104
	v_mov_b32_e32 v3, s29
	ds_write_b32 v183, v3 offset:108
	v_mov_b32_e32 v3, s30
	ds_write_b32 v183, v3 offset:112
	v_mov_b32_e32 v3, s34
	ds_write_b32 v183, v3 offset:116
	v_mov_b32_e32 v3, s35
	ds_write_b32 v183, v3 offset:120
	v_mov_b32_e32 v3, s36
	ds_write_b32 v183, v3 offset:124
	v_mov_b32_e32 v3, s37
	ds_write_b32 v183, v3 offset:128
	v_mov_b32_e32 v3, s38
	ds_write_b32 v183, v3 offset:132
	v_mov_b32_e32 v3, s39
	ds_write_b32 v183, v3 offset:136
	v_mov_b32_e32 v3, s40
	ds_write_b32 v183, v3 offset:140
	v_mov_b32_e32 v3, s41
	ds_write_b32 v183, v3 offset:144
	v_mov_b32_e32 v3, s42
	ds_write_b32 v183, v3 offset:148
	v_mov_b32_e32 v3, s43
	ds_write_b32 v183, v3 offset:152
	v_mov_b32_e32 v3, s44
	ds_write_b32 v183, v3 offset:156
	v_mov_b32_e32 v3, s45
	ds_write_b32 v183, v3 offset:160
	v_mov_b32_e32 v3, s46
	ds_write_b32 v183, v3 offset:164
	v_mov_b32_e32 v3, s47
	ds_write_b32 v183, v3 offset:168
	v_mov_b32_e32 v3, s48
	ds_write_b32 v183, v3 offset:172
	v_mov_b32_e32 v3, s49
	ds_write_b32 v183, v3 offset:176
	v_mov_b32_e32 v3, s50
	ds_write_b32 v183, v3 offset:180
	v_mov_b32_e32 v3, s51
	ds_write_b32 v183, v3 offset:184
	v_mov_b32_e32 v3, s52
	ds_write_b32 v183, v3 offset:188
	v_mov_b32_e32 v3, s53
	ds_write_b32 v183, v3 offset:192
	v_mov_b32_e32 v3, s54
	ds_write_b32 v183, v3 offset:196
	v_mov_b32_e32 v3, s55
	ds_write_b32 v183, v3 offset:200
	v_mov_b32_e32 v3, s56
	ds_write_b32 v183, v3 offset:204
	v_mov_b32_e32 v3, s57
	ds_write_b32 v183, v3 offset:208
	s_mov_b32 s52, m0
	v_mov_b32_e32 v3, s52
	ds_write_b32 v183, v3 offset:212
	v_lshrrev_b32_e32 v3, 6, v220
	s_nop 0
	v_readfirstlane_b32 s50, v3
	s_nop 3
	s_lshl_b32 s54, s50, 12
	s_add_i32 s54, s54, 0x18800
	s_load_dwordx2 s[18:19], s[70:71], 0x98
	s_load_dwordx2 s[20:21], s[70:71], 0x58
	v_and_b32_e32 v47, 31, v173
	v_lshrrev_b32_e32 v48, 5, v173
	v_lshlrev_b32_e32 v46, 4, v173
	v_mov_b32_e32 v67, 0xff800000
	v_lshlrev_b32_e32 v183, 2, v48
	v_sub_u32_e32 v54, v47, v183
	v_mov_b32_e32 v66, 0x3e38aa3b
	v_and_b32_e32 v3, 7, v47
	v_add_u32_e32 v35, 0, v48
	v_xor_b32_e32 v35, v35, v3
	v_lshlrev_b32_e32 v35, 4, v35
	v_lshl_add_u32 v35, v47, 7, v35
	v_add_u32_e32 v70, s54, v35
	v_subrev_u32_e32 v35, 0x18000, v70
	v_add_u32_e32 v36, 2, v48
	v_xor_b32_e32 v36, v36, v3
	v_lshlrev_b32_e32 v36, 4, v36
	v_lshl_add_u32 v36, v47, 7, v36
	v_add_u32_e32 v71, s54, v36
	v_subrev_u32_e32 v36, 0x18000, v71
	v_add_u32_e32 v37, 4, v48
	v_xor_b32_e32 v37, v37, v3
	v_lshlrev_b32_e32 v37, 4, v37
	v_lshl_add_u32 v37, v47, 7, v37
	v_add_u32_e32 v72, s54, v37
	v_subrev_u32_e32 v37, 0x18000, v72
	v_add_u32_e32 v38, 6, v48
	v_xor_b32_e32 v38, v38, v3
	v_lshlrev_b32_e32 v38, 4, v38
	v_lshl_add_u32 v38, v47, 7, v38
	v_add_u32_e32 v73, s54, v38
	v_subrev_u32_e32 v38, 0x18000, v73
	v_lshrrev_b32_e32 v39, 3, v173
	v_and_b32_e32 v3, 7, v173
	v_and_b32_e32 v40, 7, v39
	v_xor_b32_e32 v40, v3, v40
	v_lshlrev_b32_e32 v40, 4, v40
	v_lshrrev_b32_e32 v74, 2, v173
	v_and_b32_e32 v74, 3, v74
	v_lshl_add_u32 v74, v48, 2, v74
	v_lshlrev_b32_e32 v74, 7, v74
	v_bfe_u32 v3, v173, 4, 1
	v_lshl_add_u32 v74, v3, 5, v74
	v_and_b32_e32 v3, 3, v173
	v_lshl_add_u32 v74, v3, 3, v74
	v_add_u32_e32 v74, s54, v74
	v_subrev_u32_e32 v74, 0xc000, v74
	v_and_b32_e32 v76, 7, v173
	v_lshlrev_b32_e32 v76, 4, v76
	s_mov_b32 s0, s1
	s_waitcnt lgkmcnt(0)

.Lband_dec_done:
	s_mul_i32 s17, s23, 0x1600000
	s_add_u32 s2, s18, s17
	s_addc_u32 s3, s19, 0
	s_add_u32 s2, s2, 0x5600000
	s_addc_u32 s3, s3, 0
	s_lshl_b32 s11, 0x2c000, s9
	v_lshl_add_u32 v183, s8, 5, v47
	v_lshlrev_b32_e32 v183, s9, v183
	v_add_u32_e32 v57, s10, v183
	v_lshlrev_b32_e32 v183, s9, v39
	v_add_u32_e32 v183, s10, v183
	v_mul_u32_u24_e32 v41, 0x1600, v183
	s_lshl_b32 s57, 0x100, s1
	s_add_i32 s57, s57, s12
	v_add_u32_e32 v75, s57, v41
	v_add_u32_e32 v75, v75, v76
	v_add_u32_e32 v41, s12, v41
	v_add_u32_e32 v41, v41, v40
	s_lshl_b32 s51, 0xb000, s9
	s_sub_i32 s53, s8, s50
	s_barrier
	s_mul_i32 s17, s8, s11
	s_sub_i32 s16, s13, s12
	s_add_i32 s17, s17, s16
	v_add_u32_e32 v42, s17, v41
	v_add_u32_e32 v43, s51, v42
	v_add_u32_e32 v44, s51, v43
	v_add_u32_e32 v45, s51, v44
	s_add_i32 m0, s54, 0x0
	global_load_lds_dwordx4 v42, s[2:3]
	s_add_i32 m0, s54, 0x400
	global_load_lds_dwordx4 v43, s[2:3]
	s_add_i32 m0, s54, 0x800
	global_load_lds_dwordx4 v44, s[2:3]
	s_add_i32 m0, s54, 0xc00
	global_load_lds_dwordx4 v45, s[2:3]
	s_mul_i32 s16, s50, 3
	s_add_i32 s16, s16, 0
	s_cmp_lt_u32 s16, 12
	s_cbranch_scc0 .Lband_ldv0
	s_lshl_b32 s55, s16, 12
	s_add_i32 s55, s55, 0x800
	s_add_i32 s16, s16, s53
	s_add_i32 s16, s16, -4
	s_max_i32 s16, s16, 0
	s_mul_i32 s17, s16, s11
	v_add_u32_e32 v42, s17, v41
	v_add_u32_e32 v43, s51, v42
	v_add_u32_e32 v44, s51, v43
	v_add_u32_e32 v45, s51, v44
	s_add_i32 m0, s55, 0x0
	global_load_lds_dwordx4 v42, s[2:3]
	s_add_i32 m0, s55, 0x400
	global_load_lds_dwordx4 v43, s[2:3]
	s_add_i32 m0, s55, 0x800
	global_load_lds_dwordx4 v44, s[2:3]
	s_add_i32 m0, s55, 0xc00
	global_load_lds_dwordx4 v45, s[2:3]
	s_branch .Lband_ldd0
.Lband_ldv0:
	s_add_i32 s16, s16, -12
	s_lshl_b32 s55, s16, 12
	s_add_i32 s55, s55, 0xc800
	s_add_i32 s16, s16, s53
	s_add_i32 s16, s16, -4
	s_max_i32 s16, s16, 0
	s_mul_i32 s17, s16, s11
	v_add_u32_e32 v42, s17, v75
	v_add_u32_e32 v43, s51, v42
	v_add_u32_e32 v44, s51, v43
	v_add_u32_e32 v45, s51, v44
	s_add_i32 m0, s55, 0x0
	global_load_lds_dwordx4 v42, s[2:3]
	s_add_i32 m0, s55, 0x400
	global_load_lds_dwordx4 v43, s[2:3]
	s_add_i32 m0, s55, 0x800
	global_load_lds_dwordx4 v44, s[2:3]
	s_add_i32 m0, s55, 0xc00
	global_load_lds_dwordx4 v45, s[2:3]

.Lband_s0c:
	s_waitcnt vmcnt(0)
	s_barrier
	s_cmp_lt_i32 s8, 4
	s_cbranch_scc1 .Lband_s0b
	ds_read_b64_tr_b16 v[82:83], v74 offset:0
	ds_read_b64_tr_b16 v[84:85], v74 offset:1024
	ds_read_b64_tr_b16 v[86:87], v74 offset:2048
	ds_read_b64_tr_b16 v[88:89], v74 offset:3072
	ds_read_b64_tr_b16 v[90:91], v74 offset:64
	ds_read_b64_tr_b16 v[92:93], v74 offset:1088
	ds_read_b64_tr_b16 v[94:95], v74 offset:2112
	ds_read_b64_tr_b16 v[96:97], v74 offset:3136
	s_waitcnt lgkmcnt(0)
	s_nop 1
	v_mfma_f32_32x32x16_bf16 v[146:161], v[82:85], v[18:21], v[146:161]
	v_mfma_f32_32x32x16_bf16 v[184:199], v[90:93], v[18:21], v[184:199]
	v_mfma_f32_32x32x16_bf16 v[146:161], v[86:89], v[22:25], v[146:161]
	v_mfma_f32_32x32x16_bf16 v[184:199], v[94:97], v[22:25], v[184:199]
.Lband_s0b:
	s_cmp_lt_i32 s8, 3
	s_cbranch_scc1 .Lband_s1a
	ds_read_b128 v[2:5], v35 offset:4096
	ds_read_b128 v[6:9], v36 offset:4096
	ds_read_b128 v[10:13], v37 offset:4096
	ds_read_b128 v[14:17], v38 offset:4096
	ds_read_b64_tr_b16 v[82:83], v74 offset:4096
	ds_read_b64_tr_b16 v[84:85], v74 offset:5120
	ds_read_b64_tr_b16 v[86:87], v74 offset:6144
	ds_read_b64_tr_b16 v[88:89], v74 offset:7168
	ds_read_b64_tr_b16 v[90:91], v74 offset:4160
	ds_read_b64_tr_b16 v[92:93], v74 offset:5184
	ds_read_b64_tr_b16 v[94:95], v74 offset:6208
	ds_read_b64_tr_b16 v[96:97], v74 offset:7232
	s_waitcnt lgkmcnt(8)
	v_mfma_f32_32x32x16_bf16 v[18:33], v[2:5], v[130:133], 0
	v_mfma_f32_32x32x16_bf16 v[18:33], v[6:9], v[134:137], v[18:33]
	v_mfma_f32_32x32x16_bf16 v[18:33], v[10:13], v[138:141], v[18:33]
	v_mfma_f32_32x32x16_bf16 v[18:33], v[14:17], v[142:145], v[18:33]

.Lband_s1b:
	s_cmp_lt_i32 s8, 2
	s_cbranch_scc1 .Lband_s2a
	ds_read_b128 v[2:5], v35 offset:8192
	ds_read_b128 v[6:9], v36 offset:8192
	ds_read_b128 v[10:13], v37 offset:8192
	ds_read_b128 v[14:17], v38 offset:8192
	ds_read_b64_tr_b16 v[82:83], v74 offset:8192
	ds_read_b64_tr_b16 v[84:85], v74 offset:9216
	ds_read_b64_tr_b16 v[86:87], v74 offset:10240
	ds_read_b64_tr_b16 v[88:89], v74 offset:11264
	ds_read_b64_tr_b16 v[90:91], v74 offset:8256
	ds_read_b64_tr_b16 v[92:93], v74 offset:9280
	ds_read_b64_tr_b16 v[94:95], v74 offset:10304
	ds_read_b64_tr_b16 v[96:97], v74 offset:11328
	s_waitcnt lgkmcnt(8)
	v_mfma_f32_32x32x16_bf16 v[18:33], v[2:5], v[130:133], 0
	v_mfma_f32_32x32x16_bf16 v[18:33], v[6:9], v[134:137], v[18:33]
	v_mfma_f32_32x32x16_bf16 v[18:33], v[10:13], v[138:141], v[18:33]
	v_mfma_f32_32x32x16_bf16 v[18:33], v[14:17], v[142:145], v[18:33]

.Lband_s2b:
	s_cmp_lt_i32 s8, 1
	s_cbranch_scc1 .Lband_s3a
	ds_read_b128 v[2:5], v35 offset:12288
	ds_read_b128 v[6:9], v36 offset:12288
	ds_read_b128 v[10:13], v37 offset:12288
	ds_read_b128 v[14:17], v38 offset:12288
	ds_read_b64_tr_b16 v[82:83], v74 offset:12288
	ds_read_b64_tr_b16 v[84:85], v74 offset:13312
	ds_read_b64_tr_b16 v[86:87], v74 offset:14336
	ds_read_b64_tr_b16 v[88:89], v74 offset:15360
	ds_read_b64_tr_b16 v[90:91], v74 offset:12352
	ds_read_b64_tr_b16 v[92:93], v74 offset:13376
	ds_read_b64_tr_b16 v[94:95], v74 offset:14400
	ds_read_b64_tr_b16 v[96:97], v74 offset:15424
	s_waitcnt lgkmcnt(8)
	v_mfma_f32_32x32x16_bf16 v[18:33], v[2:5], v[130:133], 0
	v_mfma_f32_32x32x16_bf16 v[18:33], v[6:9], v[134:137], v[18:33]
	v_mfma_f32_32x32x16_bf16 v[18:33], v[10:13], v[138:141], v[18:33]
	v_mfma_f32_32x32x16_bf16 v[18:33], v[14:17], v[142:145], v[18:33]

.Lband_s3b:
	ds_read_b128 v[2:5], v35 offset:16384
	ds_read_b128 v[6:9], v36 offset:16384
	ds_read_b128 v[10:13], v37 offset:16384
	ds_read_b128 v[14:17], v38 offset:16384
	ds_read_b64_tr_b16 v[82:83], v74 offset:16384
	ds_read_b64_tr_b16 v[84:85], v74 offset:17408
	ds_read_b64_tr_b16 v[86:87], v74 offset:18432
	ds_read_b64_tr_b16 v[88:89], v74 offset:19456
	ds_read_b64_tr_b16 v[90:91], v74 offset:16448
	ds_read_b64_tr_b16 v[92:93], v74 offset:17472
	ds_read_b64_tr_b16 v[94:95], v74 offset:18496
	ds_read_b64_tr_b16 v[96:97], v74 offset:19520
	s_waitcnt lgkmcnt(8)
	v_mfma_f32_32x32x16_bf16 v[18:33], v[2:5], v[130:133], 0
	v_mfma_f32_32x32x16_bf16 v[18:33], v[6:9], v[134:137], v[18:33]
	v_mfma_f32_32x32x16_bf16 v[18:33], v[10:13], v[138:141], v[18:33]
	v_mfma_f32_32x32x16_bf16 v[18:33], v[14:17], v[142:145], v[18:33]
	v_mov_b32_e32 v53, v52
	s_nop 7
	s_nop 4
	v_pk_fma_f32 v[18:19], v[18:19], v[66:67], s[34:35] op_sel_hi:[1,0,1]
	v_pk_fma_f32 v[20:21], v[20:21], v[66:67], s[36:37] op_sel_hi:[1,0,1]
	v_pk_fma_f32 v[22:23], v[22:23], v[66:67], s[38:39] op_sel_hi:[1,0,1]
	v_pk_fma_f32 v[24:25], v[24:25], v[66:67], s[40:41] op_sel_hi:[1,0,1]
	v_pk_fma_f32 v[26:27], v[26:27], v[66:67], s[42:43] op_sel_hi:[1,0,1]
	v_pk_fma_f32 v[28:29], v[28:29], v[66:67], s[44:45] op_sel_hi:[1,0,1]
	v_pk_fma_f32 v[30:31], v[30:31], v[66:67], s[46:47] op_sel_hi:[1,0,1]
	v_pk_fma_f32 v[32:33], v[32:33], v[66:67], s[48:49] op_sel_hi:[1,0,1]
	v_cmp_le_i32_e64 s[16:17], 0, v54
	v_cmp_le_i32_e64 s[22:23], 1, v54
	v_cmp_le_i32_e64 s[24:25], 2, v54
	v_cmp_le_i32_e64 s[28:29], 3, v54
	v_cmp_le_i32_e32 vcc, 8, v54
	v_cndmask_b32_e64 v18, v67, v18, s[16:17]
	v_cndmask_b32_e64 v19, v67, v19, s[22:23]
	v_cndmask_b32_e64 v20, v67, v20, s[24:25]
	v_cndmask_b32_e64 v21, v67, v21, s[28:29]
	v_cndmask_b32_e64 v22, v67, v22, vcc
	v_cmp_le_i32_e64 s[16:17], 9, v54
	v_cmp_le_i32_e64 s[22:23], 10, v54
	v_cmp_le_i32_e64 s[24:25], 11, v54
	v_cmp_le_i32_e64 s[28:29], 16, v54
	v_cmp_le_i32_e32 vcc, 17, v54
	v_cndmask_b32_e64 v23, v67, v23, s[16:17]
	v_cndmask_b32_e64 v24, v67, v24, s[22:23]
	v_cndmask_b32_e64 v25, v67, v25, s[24:25]
	v_cndmask_b32_e64 v26, v67, v26, s[28:29]
	v_cndmask_b32_e64 v27, v67, v27, vcc
	v_cmp_le_i32_e64 s[16:17], 18, v54
	v_cmp_le_i32_e64 s[22:23], 19, v54
	v_cmp_le_i32_e64 s[24:25], 24, v54
	v_cmp_le_i32_e64 s[28:29], 25, v54
	v_cmp_le_i32_e32 vcc, 26, v54
	v_cndmask_b32_e64 v28, v67, v28, s[16:17]
	v_cndmask_b32_e64 v29, v67, v29, s[22:23]
	v_cndmask_b32_e64 v30, v67, v30, s[24:25]
	v_cndmask_b32_e64 v31, v67, v31, s[28:29]
	v_cndmask_b32_e64 v32, v67, v32, vcc
	v_cmp_le_i32_e64 s[16:17], 27, v54
	s_nop 1
	v_cndmask_b32_e64 v33, v67, v33, s[16:17]
	v_max3_f32 v183, v18, v19, v20
	v_max3_f32 v64, v21, v22, v23
	v_max3_f32 v60, v24, v25, v26
	v_max3_f32 v61, v27, v28, v29
	v_max3_f32 v68, v30, v31, v32
	v_max3_f32 v183, v183, v64, v60
	v_max3_f32 v61, v61, v68, v33
	v_max_f32_e32 v183, v183, v61
	v_add_f32_e32 v183, v183, v53
	v_mov_b32_e32 v64, v183
	s_nop 1
	v_permlane32_swap_b32_e32 v64, v183
	v_max_f32_e32 v183, v183, v64
	v_cmp_lt_f32_e32 vcc, v34, v183
	s_cbranch_vccz .Lband_keep4
	v_max_f32_e32 v64, v49, v183
	v_sub_f32_e32 v60, v49, v64
	v_exp_f32_e32 v60, v60
	v_mov_b32_e32 v49, v64
	v_add_f32_e32 v34, 0x41a00000, v64
	v_mul_f32_e32 v50, v50, v60
	v_pk_mul_f32 v[146:147], v[146:147], v[60:61] op_sel_hi:[1,0]
	v_pk_mul_f32 v[148:149], v[148:149], v[60:61] op_sel_hi:[1,0]
	v_pk_mul_f32 v[150:151], v[150:151], v[60:61] op_sel_hi:[1,0]
	v_pk_mul_f32 v[152:153], v[152:153], v[60:61] op_sel_hi:[1,0]
	v_pk_mul_f32 v[154:155], v[154:155], v[60:61] op_sel_hi:[1,0]
	v_pk_mul_f32 v[156:157], v[156:157], v[60:61] op_sel_hi:[1,0]
	v_pk_mul_f32 v[158:159], v[158:159], v[60:61] op_sel_hi:[1,0]
	v_pk_mul_f32 v[160:161], v[160:161], v[60:61] op_sel_hi:[1,0]
	v_pk_mul_f32 v[184:185], v[184:185], v[60:61] op_sel_hi:[1,0]
	v_pk_mul_f32 v[186:187], v[186:187], v[60:61] op_sel_hi:[1,0]
	v_pk_mul_f32 v[188:189], v[188:189], v[60:61] op_sel_hi:[1,0]
	v_pk_mul_f32 v[190:191], v[190:191], v[60:61] op_sel_hi:[1,0]
	v_pk_mul_f32 v[192:193], v[192:193], v[60:61] op_sel_hi:[1,0]
	v_pk_mul_f32 v[194:195], v[194:195], v[60:61] op_sel_hi:[1,0]
	v_pk_mul_f32 v[196:197], v[196:197], v[60:61] op_sel_hi:[1,0]
	v_pk_mul_f32 v[198:199], v[198:199], v[60:61] op_sel_hi:[1,0]

.Lband_epi_scale:
	v_pk_mul_f32 v[146:147], v[146:147], v[60:61] op_sel_hi:[1,0]
	v_pk_mul_f32 v[148:149], v[148:149], v[60:61] op_sel_hi:[1,0]
	v_pk_mul_f32 v[150:151], v[150:151], v[60:61] op_sel_hi:[1,0]
	v_pk_mul_f32 v[152:153], v[152:153], v[60:61] op_sel_hi:[1,0]
	v_pk_mul_f32 v[154:155], v[154:155], v[60:61] op_sel_hi:[1,0]
	v_pk_mul_f32 v[156:157], v[156:157], v[60:61] op_sel_hi:[1,0]
	v_pk_mul_f32 v[158:159], v[158:159], v[60:61] op_sel_hi:[1,0]
	v_pk_mul_f32 v[160:161], v[160:161], v[60:61] op_sel_hi:[1,0]
	v_pk_mul_f32 v[184:185], v[184:185], v[60:61] op_sel_hi:[1,0]
	v_pk_mul_f32 v[186:187], v[186:187], v[60:61] op_sel_hi:[1,0]
	v_pk_mul_f32 v[188:189], v[188:189], v[60:61] op_sel_hi:[1,0]
	v_pk_mul_f32 v[190:191], v[190:191], v[60:61] op_sel_hi:[1,0]
	v_pk_mul_f32 v[192:193], v[192:193], v[60:61] op_sel_hi:[1,0]
	v_pk_mul_f32 v[194:195], v[194:195], v[60:61] op_sel_hi:[1,0]
	v_pk_mul_f32 v[196:197], v[196:197], v[60:61] op_sel_hi:[1,0]
	v_pk_mul_f32 v[198:199], v[198:199], v[60:61] op_sel_hi:[1,0]
	v_lshl_add_u32 v62, v48, 3, v62
	v_cvt_pk_bf16_f32 v146, v146, v147
	v_cvt_pk_bf16_f32 v147, v148, v149
	v_cvt_pk_bf16_f32 v148, v150, v151
	v_cvt_pk_bf16_f32 v149, v152, v153
	s_nop 1
	v_permlane32_swap_b32_e32 v146, v148
	v_permlane32_swap_b32_e32 v147, v149
	global_store_dwordx4 v62, v[146:149], s[6:7]
	v_cvt_pk_bf16_f32 v154, v154, v155
	v_cvt_pk_bf16_f32 v155, v156, v157
	v_cvt_pk_bf16_f32 v156, v158, v159
	v_cvt_pk_bf16_f32 v157, v160, v161
	s_nop 1
	v_permlane32_swap_b32_e32 v154, v156
	v_permlane32_swap_b32_e32 v155, v157
	global_store_dwordx4 v62, v[154:157], s[6:7] offset:32
	v_cvt_pk_bf16_f32 v184, v184, v185
	v_cvt_pk_bf16_f32 v185, v186, v187
	v_cvt_pk_bf16_f32 v186, v188, v189
	v_cvt_pk_bf16_f32 v187, v190, v191
	s_nop 1
	v_permlane32_swap_b32_e32 v184, v186
	v_permlane32_swap_b32_e32 v185, v187
	global_store_dwordx4 v62, v[184:187], s[6:7] offset:64
	v_cvt_pk_bf16_f32 v192, v192, v193
	v_cvt_pk_bf16_f32 v193, v194, v195
	v_cvt_pk_bf16_f32 v194, v196, v197
	v_cvt_pk_bf16_f32 v195, v198, v199
	s_nop 1
	v_permlane32_swap_b32_e32 v192, v194
	v_permlane32_swap_b32_e32 v193, v195
	global_store_dwordx4 v62, v[192:195], s[6:7] offset:96
	s_add_i32 s0, s0, s68
	s_cmp_lt_u32 s0, 0x4000
	s_cbranch_scc1 .Lband_item
	v_lshlrev_b32_e32 v183, 2, v220
	v_add_u32_e32 v2, 0x10000, v183
	v_lshrrev_b32_e32 v183, 6, v220
	v_lshlrev_b32_e32 v183, 8, v183
	v_add_u32_e32 v183, 0x0, v183
	ds_read_b32 v2, v183 offset:0
	ds_read_b32 v3, v183 offset:4
	ds_read_b32 v4, v183 offset:8
	ds_read_b32 v5, v183 offset:12
	ds_read_b32 v6, v183 offset:16
	ds_read_b32 v7, v183 offset:20
	ds_read_b32 v8, v183 offset:24
	ds_read_b32 v9, v183 offset:28
	ds_read_b32 v10, v183 offset:32
	ds_read_b32 v11, v183 offset:36
	ds_read_b32 v12, v183 offset:40
	ds_read_b32 v13, v183 offset:44
	ds_read_b32 v14, v183 offset:48
	ds_read_b32 v15, v183 offset:52
	ds_read_b32 v16, v183 offset:56
	ds_read_b32 v17, v183 offset:60
	ds_read_b32 v18, v183 offset:64
	ds_read_b32 v19, v183 offset:68
	ds_read_b32 v20, v183 offset:72
	ds_read_b32 v21, v183 offset:76
	ds_read_b32 v22, v183 offset:80
	ds_read_b32 v23, v183 offset:84
	ds_read_b32 v24, v183 offset:88
	ds_read_b32 v25, v183 offset:92
	ds_read_b32 v26, v183 offset:96
	ds_read_b32 v27, v183 offset:100
	ds_read_b32 v28, v183 offset:104
	ds_read_b32 v29, v183 offset:108
	ds_read_b32 v30, v183 offset:112
	ds_read_b32 v31, v183 offset:116
	ds_read_b32 v32, v183 offset:120
	ds_read_b32 v33, v183 offset:124
	ds_read_b32 v34, v183 offset:128
	ds_read_b32 v35, v183 offset:132
	ds_read_b32 v36, v183 offset:136
	ds_read_b32 v37, v183 offset:140
	ds_read_b32 v38, v183 offset:144
	ds_read_b32 v39, v183 offset:148
	ds_read_b32 v40, v183 offset:152
	ds_read_b32 v41, v183 offset:156
	ds_read_b32 v42, v183 offset:160
	ds_read_b32 v43, v183 offset:164
	ds_read_b32 v44, v183 offset:168
	ds_read_b32 v45, v183 offset:172
	ds_read_b32 v46, v183 offset:176
	ds_read_b32 v47, v183 offset:180
	ds_read_b32 v48, v183 offset:184
	ds_read_b32 v49, v183 offset:188
	ds_read_b32 v50, v183 offset:192
	ds_read_b32 v51, v183 offset:196
	ds_read_b32 v52, v183 offset:200
	ds_read_b32 v53, v183 offset:204
	ds_read_b32 v54, v183 offset:208
	ds_read_b32 v55, v183 offset:212
	s_waitcnt lgkmcnt(0)
	v_readfirstlane_b32 s52, v55
	s_nop 3
	s_mov_b32 m0, s52
	v_readfirstlane_b32 s2, v2
	v_readfirstlane_b32 s3, v3
	v_readfirstlane_b32 s4, v4
	v_readfirstlane_b32 s5, v5
	v_readfirstlane_b32 s6, v6
	v_readfirstlane_b32 s7, v7
	v_readfirstlane_b32 s8, v8
	v_readfirstlane_b32 s9, v9
	v_readfirstlane_b32 s10, v10
	v_readfirstlane_b32 s11, v11
	v_readfirstlane_b32 s12, v12
	v_readfirstlane_b32 s13, v13
	v_readfirstlane_b32 s14, v14
	v_readfirstlane_b32 s15, v15
	v_readfirstlane_b32 s16, v16
	v_readfirstlane_b32 s17, v17
	v_readfirstlane_b32 s18, v18
	v_readfirstlane_b32 s19, v19
	v_readfirstlane_b32 s20, v20
	v_readfirstlane_b32 s21, v21
	v_readfirstlane_b32 s22, v22
	v_readfirstlane_b32 s23, v23
	v_readfirstlane_b32 s24, v24
	v_readfirstlane_b32 s25, v25
	v_readfirstlane_b32 s26, v26
	v_readfirstlane_b32 s27, v27
	v_readfirstlane_b32 s28, v28
	v_readfirstlane_b32 s29, v29
	v_readfirstlane_b32 s30, v30
	v_readfirstlane_b32 s34, v31
	v_readfirstlane_b32 s35, v32
	v_readfirstlane_b32 s36, v33
	v_readfirstlane_b32 s37, v34
	v_readfirstlane_b32 s38, v35
	v_readfirstlane_b32 s39, v36
	v_readfirstlane_b32 s40, v37
	v_readfirstlane_b32 s41, v38
	v_readfirstlane_b32 s42, v39
	v_readfirstlane_b32 s43, v40
	v_readfirstlane_b32 s44, v41
	v_readfirstlane_b32 s45, v42
	v_readfirstlane_b32 s46, v43
	v_readfirstlane_b32 s47, v44
	v_readfirstlane_b32 s48, v45
	v_readfirstlane_b32 s49, v46
	v_readfirstlane_b32 s50, v47
	v_readfirstlane_b32 s51, v48
	v_readfirstlane_b32 s52, v49
	v_readfirstlane_b32 s53, v50
	v_readfirstlane_b32 s54, v51
	v_readfirstlane_b32 s55, v52
	v_readfirstlane_b32 s56, v53
	v_readfirstlane_b32 s57, v54
	s_waitcnt vmcnt(0)
	s_branch .Lband_exit
